# combined: scan next-chunk operands consumed at next header + W_up LDS-DMA staging 4+4 per super-phase, on top of EpiR, attention tail, scan and gdn_prep load batching
# speedup vs baseline: 1.0033x; 1.0033x over previous
; DI unsigned pk2(float lo, float hi) { const f32x2 v = {lo, hi}; const bf16x2_t b = __builtin_convertvector(v, bf16x2_t); return __builtin_bit_cast(unsigned, b); }
; template <int C> DI void gdn_scan_item(const Params& p, int l, int b, int h, unsigned char* smem) {
;     ...
;     f32x4 S[8];
;     float* sout = SMP ? p.out + O_STS + (size_t)((l * 8 + b) * 4 + h) * 16384 : p.out + O_STP + (size_t)((l * 4 + b) * 4 + h) * 16384;
;     if (SMP) { const float* s0 = p.in[4] + (size_t)((l * 8 + b) * 4 + h) * 16384;
; #pragma unroll
;         for (int c = 0; c < 8; ++c)
; #pragma unroll
;             for (int r = 0; r < 4; ++r) S[c][r] = s0[(16 * w + 4 * gq + r) * 128 + 16 * c + l15]; }
;     else {
; #pragma unroll
;         for (int c = 0; c < 8; ++c) S[c] = (f32x4){0.f, 0.f, 0.f, 0.f}; }
; #pragma unroll
;     for (int c = 0; c < 8; ++c) { u32x2 o; o.x = pk2(S[c][0], S[c][1]); o.y = pk2(S[c][2], S[c][3]); *(u32x2*)(SbT + (16 * c + l15) * 144 + 16 * w + 4 * gq) = o; }
;     __syncthreads();
;     const int nch = SMP ? 1 : 64;
;     bf16x8 cW[4], cQ[4]; float cU[TPW][4];
;     ...
;     { SCAN_PTRS(0)
; #pragma unroll
;       for (int s = 0; s < 4; ++s) { cW[s] = *(const bf16x8*)(Wo + (16 * ti + l15) * 128 + 32 * s + 8 * gq); cQ[s] = *(const bf16x8*)(QG + (16 * ti + l15) * 128 + 32 * s + 8 * gq); }
; #pragma unroll
;       for (int t = 0; t < TPW; ++t)
; #pragma unroll
;           for (int r = 0; r < 4; ++r) cU[t][r] = U[(16 * ti + 4 * gq + r) * 128 + 16 * (dvg * TPW + t) + l15]; }
.LBB0_677:
	s_or_b64 exec, exec, s[0:1]
	v_readlane_b32 s0, v253, 16
	v_readlane_b32 s1, v253, 17
	s_lshl_b32 s76, s43, 7
	s_and_b64 vcc, exec, s[0:1]
	s_waitcnt lgkmcnt(0)
	s_barrier
	s_cbranch_vccz .LBB0_685
	v_readlane_b32 s0, v254, 47
	v_readlane_b32 s1, v254, 48
	s_load_dwordx2 s[4:5], s[0:1], 0x78
	s_load_dwordx4 s[8:11], s[0:1], 0xd0
	v_mov_b32_e32 v0, v143
	s_lshl_b64 s[0:1], s[76:77], 2
	v_ashrrev_i32_e32 v145, 6, v0
	v_lshrrev_b32_e32 v1, 30, v145
	v_bfe_u32 v153, v0, 4, 2
	v_add_u32_e32 v1, v145, v1
	v_and_b32_e32 v151, 15, v0
	s_waitcnt lgkmcnt(0)
	s_add_u32 s12, s4, s0
	v_lshlrev_b32_e32 v2, 5, v145
	v_lshlrev_b32_e32 v0, 3, v153
	s_mov_b32 s0, 0
	v_ashrrev_i32_e32 v10, 2, v1
	s_addc_u32 s13, s5, s1
	v_add3_u32 v16, 0, v2, v0
	s_movk_i32 s17, 0x120
	s_mov_b32 s1, s0
	v_mul_i32_i24_e32 v14, 4, v10
	v_mad_u32_u24 v4, v151, s17, v16
	v_mov_b64_e32 v[2:3], s[0:1]
	s_add_u32 s1, s10, 0xc101000
	v_sub_u32_e32 v15, v145, v14
	ds_write2st64_b64 v4, v[2:3], v[2:3] offset1:9
	ds_write2st64_b64 v4, v[2:3], v[2:3] offset0:18 offset1:27
	ds_write2st64_b64 v4, v[2:3], v[2:3] offset0:36 offset1:45
	ds_write2st64_b64 v4, v[2:3], v[2:3] offset0:54 offset1:63
	s_addc_u32 s16, s11, 0
	v_readlane_b32 s14, v254, 1
	v_lshlrev_b32_e32 v2, 7, v151
	v_readlane_b32 s15, v254, 2
	s_add_u32 s4, s1, s14
	v_lshl_or_b32 v112, v15, 11, v2
	s_addc_u32 s5, s16, s15
	v_ashrrev_i32_e32 v113, 31, v112
	v_lshl_add_u64 v[2:3], v[112:113], 1, s[4:5]
	v_lshlrev_b32_e32 v140, 4, v153
	v_lshl_add_u64 v[2:3], v[2:3], 0, v[140:141]
	s_mov_b64 s[6:7], 0x8000
	v_add_co_u32_e32 v8, vcc, s60, v2
	v_lshl_add_u64 v[4:5], v[2:3], 0, s[6:7]
	s_mov_b64 s[6:7], 0xc000
	v_addc_co_u32_e32 v9, vcc, 0, v3, vcc
	v_lshl_add_u64 v[6:7], v[2:3], 0, s[6:7]
	v_add_co_u32_e32 v2, vcc, s82, v2
	s_waitcnt lgkmcnt(0)
	s_barrier
	v_addc_co_u32_e32 v3, vcc, 0, v3, vcc
	global_load_dwordx4 v[104:107], v[8:9], off
	global_load_dwordx4 v[100:103], v[2:3], off
	global_load_dwordx4 v[92:95], v[4:5], off offset:64
	global_load_dwordx4 v[84:87], v[4:5], off offset:128
	global_load_dwordx4 v[88:91], v[6:7], off offset:64
	global_load_dwordx4 v[76:79], v[4:5], off offset:192
	global_load_dwordx4 v[80:83], v[6:7], off offset:128
	global_load_dwordx4 v[72:75], v[6:7], off offset:192
	v_lshlrev_b32_e32 v18, 2, v153
	v_lshlrev_b32_e32 v2, 6, v10
	v_lshl_or_b32 v5, v15, 4, v18
	v_or_b32_e32 v4, v2, v151
	v_lshl_add_u32 v114, v5, 7, v4
	v_or_b32_e32 v19, 1, v5
	v_or_b32_e32 v20, 2, v5
	v_or_b32_e32 v21, 3, v5
	v_ashrrev_i32_e32 v115, 31, v114
	v_lshl_add_u32 v116, v19, 7, v4
	v_lshl_add_u32 v118, v20, 7, v4
	v_lshl_add_u32 v120, v21, 7, v4
	v_lshl_add_u64 v[6:7], v[114:115], 2, s[4:5]
	v_ashrrev_i32_e32 v117, 31, v116
	v_ashrrev_i32_e32 v119, 31, v118
	v_ashrrev_i32_e32 v121, 31, v120
	v_lshl_add_u64 v[8:9], v[116:117], 2, s[4:5]
	v_lshl_add_u64 v[10:11], v[118:119], 2, s[4:5]
	v_lshl_add_u64 v[12:13], v[120:121], 2, s[4:5]
	global_load_dword v168, v[6:7], off
	global_load_dword v169, v[8:9], off
	global_load_dword v164, v[6:7], off offset:64
	global_load_dword v165, v[8:9], off offset:64
	global_load_dword v160, v[6:7], off offset:128
	global_load_dword v161, v[8:9], off offset:128
	global_load_dword v157, v[8:9], off offset:192
	global_load_dword v156, v[6:7], off offset:192
	global_load_dword v170, v[10:11], off
	global_load_dword v171, v[12:13], off
	global_load_dword v166, v[10:11], off offset:64
	global_load_dword v167, v[12:13], off offset:64
	global_load_dword v162, v[10:11], off offset:128
	global_load_dword v163, v[12:13], off offset:128
	global_load_dword v159, v[12:13], off offset:192
	global_load_dword v158, v[10:11], off offset:192
	v_lshlrev_b32_e32 v3, 5, v15
	v_and_b32_e32 v10, 64, v205
	v_add3_u32 v9, 0, v3, v0
	v_xor_b32_e32 v3, 1, v205
	v_add_u32_e32 v10, 64, v10
	v_cmp_lt_i32_e32 vcc, v3, v10
	v_readlane_b32 s4, v253, 19
	s_lshl_b32 s4, s4, 1
	v_cndmask_b32_e32 v3, v205, v3, vcc
	v_lshlrev_b32_e32 v172, 2, v3
	v_xor_b32_e32 v3, 2, v205
	v_cmp_lt_i32_e32 vcc, v3, v10
	s_add_u32 s4, s10, s4
	v_lshlrev_b32_e32 v6, 1, v151
	v_cndmask_b32_e32 v3, v205, v3, vcc
	v_lshlrev_b32_e32 v173, 2, v3
	v_xor_b32_e32 v3, 4, v205
	v_cmp_lt_i32_e32 vcc, v3, v10
	v_mov_b32_e32 v7, v141
	s_addc_u32 s5, s11, 0
	v_cndmask_b32_e32 v3, v205, v3, vcc
	v_lshlrev_b32_e32 v174, 2, v3
	v_xor_b32_e32 v3, 8, v205
	v_cmp_lt_i32_e32 vcc, v3, v10
	v_lshl_add_u64 v[6:7], s[4:5], 0, v[6:7]
	v_and_b32_e32 v1, -4, v1
	v_cndmask_b32_e32 v3, v205, v3, vcc
	v_lshlrev_b32_e32 v175, 2, v3
	v_ashrrev_i32_e32 v3, 31, v2
	v_lshl_add_u64 v[2:3], v[2:3], 1, v[6:7]
	s_mov_b64 s[18:19], 0x19441c00
	v_lshlrev_b32_e32 v178, 4, v5
	v_ashrrev_i32_e32 v5, 31, v4
	v_lshlrev_b32_e32 v8, 6, v151
	v_add_u32_e32 v176, 0, v1
	v_lshl_add_u64 v[122:123], v[2:3], 0, s[18:19]
	v_mul_lo_u32 v1, v4, s17
	s_movk_i32 s17, 0xa0
	v_lshl_add_u64 v[2:3], v[4:5], 1, s[4:5]
	s_mov_b64 s[4:5], 0x5f81400
	v_mul_lo_u32 v177, v4, s17
	v_lshl_add_u64 v[124:125], v[4:5], 2, s[12:13]
	v_lshl_add_u64 v[126:127], v[2:3], 0, s[4:5]
	v_lshlrev_b32_e32 v2, 4, v145
	v_readlane_b32 s4, v253, 18
	v_lshl_or_b32 v4, v145, 10, v8
	v_lshlrev_b32_e32 v5, 10, v14
	v_add3_u32 v2, s4, v2, v18
	v_lshlrev_b32_e32 v3, 4, v14
	v_sub_u32_e32 v6, v4, v5
	v_mul_u32_u24_e32 v17, 0x120, v151
	v_add_u32_e32 v155, 0, v140
	v_mul_u32_u24_e32 v10, 0xa0, v151
	v_sub_u32_e32 v182, v2, v3
	v_lshl_add_u64 v[2:3], s[14:15], 0, v[140:141]
	v_ashrrev_i32_e32 v7, 31, v6
	v_ashrrev_i32_e32 v5, 31, v4
	v_lshlrev_b32_e32 v179, 4, v19
	v_lshlrev_b32_e32 v180, 4, v20
	v_lshlrev_b32_e32 v181, 4, v21
	v_lshl_add_u64 v[128:129], v[6:7], 1, v[2:3]
	v_lshl_add_u64 v[130:131], v[4:5], 1, v[2:3]
	v_mov_b32_e32 v32, 0
	v_lshlrev_b32_e32 v140, 1, v0
	v_add_u32_e32 v183, v155, v1
	v_add_u32_e32 v184, v9, v177
	v_add_u32_e32 v185, v155, v10
	v_add_u32_e32 v186, v16, v17
	v_readlane_b32 s12, v254, 26
	s_waitcnt vmcnt(18)
; #define MFMA16(a, b, c) __builtin_amdgcn_mfma_f32_16x16x32_bf16((a), (b), (c), 0, 0, 0)
; DI unsigned pk2(float lo, float hi) { const f32x2 v = {lo, hi}; const bf16x2_t b = __builtin_convertvector(v, bf16x2_t); return __builtin_bit_cast(unsigned, b); }
; template <int C> DI void gdn_scan_item(const Params& p, int l, int b, int h, unsigned char* smem) {
;     ...
;     { SCAN_PTRS(0)
; #pragma unroll
;       for (int s = 0; s < 4; ++s) { cW[s] = *(const bf16x8*)(Wo + (16 * ti + l15) * 128 + 32 * s + 8 * gq); cQ[s] = *(const bf16x8*)(QG + (16 * ti + l15) * 128 + 32 * s + 8 * gq); }
; #pragma unroll
;       for (int t = 0; t < TPW; ++t)
; #pragma unroll
;           for (int r = 0; r < 4; ++r) cU[t][r] = U[(16 * ti + 4 * gq + r) * 128 + 16 * (dvg * TPW + t) + l15]; }
;     ...
;         for (int c = 0; c < 8; ++c) S[c] = S[c] * eg;
; #pragma unroll
;         for (int s = 0; s < KS2; ++s) {
; #pragma unroll
;             for (int c = 0; c < 8; ++c) { const bf16x8 bb = *(const bf16x8*)(VnT + (16 * c + l15) * 80 + 32 * s + 8 * gq); S[c] = MFMA16(aT[s], bb, S[c]); } }
; #pragma unroll
;         for (int c = 0; c < 8; ++c) { u32x2 o; o.x = pk2(S[c][0], S[c][1]); o.y = pk2(S[c][2], S[c][3]); *(u32x2*)(SbT + (16 * c + l15) * 144 + 16 * w + 4 * gq) = o; }
	v_mov_b64_e32 v[12:13], v[76:77]
	v_mov_b64_e32 v[8:9], v[84:85]
	v_mov_b64_e32 v[4:5], v[92:93]
	v_mov_b64_e32 v[0:1], v[104:105]
	s_waitcnt vmcnt(16)
	v_mov_b64_e32 v[24:25], v[72:73]
	v_mov_b64_e32 v[28:29], v[80:81]
	v_mov_b64_e32 v[20:21], v[88:89]
	v_mov_b64_e32 v[16:17], v[100:101]
	v_cmp_eq_u32_e64 s[6:7], 0, v151
	v_readlane_b32 s13, v254, 27
	v_readlane_b32 s17, v254, 5
	v_mov_b32_e32 v33, v32
	v_mov_b32_e32 v34, v32
	v_mov_b32_e32 v35, v32
	v_mov_b32_e32 v36, v32
	v_mov_b32_e32 v37, v32
	v_mov_b32_e32 v38, v32
	v_mov_b32_e32 v39, v32
	v_mov_b32_e32 v40, v32
	v_mov_b32_e32 v41, v32
	v_mov_b32_e32 v42, v32
	v_mov_b32_e32 v43, v32
	v_mov_b32_e32 v44, v32
	v_mov_b32_e32 v45, v32
	v_mov_b32_e32 v46, v32
	v_mov_b32_e32 v47, v32
	v_mov_b32_e32 v48, v32
	v_mov_b32_e32 v49, v32
	v_mov_b32_e32 v50, v32
	v_mov_b32_e32 v51, v32
	v_mov_b32_e32 v52, v32
	v_mov_b32_e32 v53, v32
	v_mov_b32_e32 v54, v32
	v_mov_b32_e32 v55, v32
	v_mov_b32_e32 v56, v32
	v_mov_b32_e32 v57, v32
	v_mov_b32_e32 v58, v32
	v_mov_b32_e32 v59, v32
	v_mov_b32_e32 v60, v32
	v_mov_b32_e32 v61, v32
	v_mov_b32_e32 v62, v32
	v_mov_b32_e32 v63, v32
	v_mov_b64_e32 v[14:15], v[78:79]
	v_mov_b64_e32 v[10:11], v[86:87]
	v_mov_b64_e32 v[6:7], v[94:95]
	v_mov_b64_e32 v[2:3], v[106:107]
	v_mov_b64_e32 v[26:27], v[74:75]
	v_mov_b64_e32 v[30:31], v[82:83]
	v_mov_b64_e32 v[22:23], v[90:91]
	v_mov_b64_e32 v[18:19], v[102:103]
	global_load_dword v144, v[124:125], off
	global_load_dword v204, v[124:125], off offset:64
	global_load_dword v227, v[124:125], off offset:128
	global_load_dword v124, v[124:125], off offset:192
	s_waitcnt vmcnt(0)
	v_mov_b32_e32 v197, v170
	v_mov_b32_e32 v198, v171
	v_mov_b32_e32 v187, v168
	v_mov_b32_e32 v188, v169
	v_mov_b32_e32 v199, v166
	v_mov_b32_e32 v209, v167
	v_mov_b32_e32 v189, v164
	v_mov_b32_e32 v190, v165
	v_mov_b32_e32 v210, v162
	v_mov_b32_e32 v211, v163
	v_mov_b32_e32 v192, v160
	v_mov_b32_e32 v193, v161
	v_mov_b32_e32 v213, v158
	v_mov_b32_e32 v212, v159
	v_mov_b32_e32 v196, v156
	v_mov_b32_e32 v195, v157
	s_branch .LBB0_680
.LBB0_679:
	s_or_b64 exec, exec, s[14:15]
	s_waitcnt lgkmcnt(0)
	ds_read_b128 v[88:91], v185 offset:36864
	ds_read_b128 v[92:95], v185 offset:39424
	ds_read_b128 v[96:99], v185 offset:41984
	ds_read_b128 v[100:103], v185 offset:44544
	ds_read_b128 v[104:107], v185 offset:47104
	ds_read_b128 v[108:111], v185 offset:49664
	v_pk_mul_f32 v[34:35], v[34:35], v[154:155] op_sel_hi:[1,0]
	v_pk_mul_f32 v[32:33], v[32:33], v[154:155] op_sel_hi:[1,0]
	v_pk_mul_f32 v[38:39], v[38:39], v[154:155] op_sel_hi:[1,0]
	v_pk_mul_f32 v[36:37], v[36:37], v[154:155] op_sel_hi:[1,0]
	v_pk_mul_f32 v[42:43], v[42:43], v[154:155] op_sel_hi:[1,0]
	v_pk_mul_f32 v[40:41], v[40:41], v[154:155] op_sel_hi:[1,0]
	v_pk_mul_f32 v[46:47], v[46:47], v[154:155] op_sel_hi:[1,0]
	v_pk_mul_f32 v[44:45], v[44:45], v[154:155] op_sel_hi:[1,0]
	v_pk_mul_f32 v[50:51], v[50:51], v[154:155] op_sel_hi:[1,0]
	v_pk_mul_f32 v[48:49], v[48:49], v[154:155] op_sel_hi:[1,0]
	v_pk_mul_f32 v[54:55], v[54:55], v[154:155] op_sel_hi:[1,0]
	v_pk_mul_f32 v[52:53], v[52:53], v[154:155] op_sel_hi:[1,0]
	v_pk_mul_f32 v[58:59], v[58:59], v[154:155] op_sel_hi:[1,0]
	v_pk_mul_f32 v[56:57], v[56:57], v[154:155] op_sel_hi:[1,0]
	v_pk_mul_f32 v[62:63], v[62:63], v[154:155] op_sel_hi:[1,0]
	v_pk_mul_f32 v[60:61], v[60:61], v[154:155] op_sel_hi:[1,0]
	s_mov_b32 s4, 0x358637bd
	s_add_i32 s0, s0, 64
	s_add_i32 s17, s17, 1
	s_waitcnt vmcnt(41) lgkmcnt(5)
	v_mfma_f32_16x16x32_bf16 v[32:35], v[68:71], v[88:91], v[32:35]
	ds_read_b128 v[88:91], v185 offset:52224
	s_waitcnt lgkmcnt(5)
	v_mfma_f32_16x16x32_bf16 v[36:39], v[68:71], v[92:95], v[36:39]
	ds_read_b128 v[92:95], v185 offset:54784
	s_waitcnt lgkmcnt(5)
	v_mfma_f32_16x16x32_bf16 v[40:43], v[68:71], v[96:99], v[40:43]
	s_waitcnt lgkmcnt(4)
	v_mfma_f32_16x16x32_bf16 v[44:47], v[68:71], v[100:103], v[44:47]
	s_waitcnt lgkmcnt(3)
	v_mfma_f32_16x16x32_bf16 v[48:51], v[68:71], v[104:107], v[48:51]
	s_waitcnt lgkmcnt(2)
	v_mfma_f32_16x16x32_bf16 v[52:55], v[68:71], v[108:111], v[52:55]
	s_waitcnt lgkmcnt(1)
	v_mfma_f32_16x16x32_bf16 v[56:59], v[68:71], v[88:91], v[56:59]
	s_waitcnt lgkmcnt(0)
	v_mfma_f32_16x16x32_bf16 v[60:63], v[68:71], v[92:95], v[60:63]
	ds_read_b128 v[68:71], v185 offset:36928
	ds_read_b128 v[88:91], v185 offset:39488
	s_add_u32 s12, s12, 4
	s_addc_u32 s13, s13, 0
	s_waitcnt vmcnt(40) lgkmcnt(1)
	v_mfma_f32_16x16x32_bf16 v[32:35], v[64:67], v[68:71], v[32:35]
	ds_read_b128 v[68:71], v185 offset:42048
	ds_read_b128 v[92:95], v185 offset:44608
	ds_read_b128 v[96:99], v185 offset:47168
	s_cmpk_lg_i32 s0, 0x1000
	s_waitcnt vmcnt(24)
	s_waitcnt lgkmcnt(3)
	v_mfma_f32_16x16x32_bf16 v[36:39], v[64:67], v[88:91], v[36:39]
	ds_read_b128 v[88:91], v185 offset:49728
	ds_read_b128 v[100:103], v185 offset:52288
	ds_read_b128 v[104:107], v185 offset:54848
	s_waitcnt lgkmcnt(5)
	v_mfma_f32_16x16x32_bf16 v[40:43], v[64:67], v[68:71], v[40:43]
	v_cvt_pk_bf16_f32 v68, v32, v33
	v_cvt_pk_bf16_f32 v69, v34, v35
	v_cvt_pk_bf16_f32 v70, v36, v37
	s_waitcnt lgkmcnt(4)
	v_mfma_f32_16x16x32_bf16 v[44:47], v[64:67], v[92:95], v[44:47]
	v_cvt_pk_bf16_f32 v71, v38, v39
	ds_write2st64_b64 v186, v[68:69], v[70:71] offset1:9
	s_nop 0
	v_cvt_pk_bf16_f32 v68, v40, v41
	s_waitcnt lgkmcnt(4)
	v_mfma_f32_16x16x32_bf16 v[48:51], v[64:67], v[96:99], v[48:51]
	v_cvt_pk_bf16_f32 v69, v42, v43
	s_nop 0
	v_cvt_pk_bf16_f32 v70, v44, v45
	v_cvt_pk_bf16_f32 v71, v46, v47
	s_waitcnt lgkmcnt(3)
	v_mfma_f32_16x16x32_bf16 v[52:55], v[64:67], v[88:91], v[52:55]
	ds_write2st64_b64 v186, v[68:69], v[70:71] offset0:18 offset1:27
	s_nop 0
	v_cvt_pk_bf16_f32 v68, v48, v49
	v_cvt_pk_bf16_f32 v69, v50, v51
	s_waitcnt lgkmcnt(3)
	v_mfma_f32_16x16x32_bf16 v[56:59], v[64:67], v[100:103], v[56:59]
	v_lshlrev_b32_e32 v96, 16, v226
	s_nop 0
	v_cvt_pk_bf16_f32 v70, v52, v53
	v_cvt_pk_bf16_f32 v71, v54, v55
	s_waitcnt lgkmcnt(2)
	v_mfma_f32_16x16x32_bf16 v[60:63], v[64:67], v[104:107], v[60:63]
	ds_write2st64_b64 v186, v[68:69], v[70:71] offset0:36 offset1:45
	s_nop 0
	v_cvt_pk_bf16_f32 v64, v56, v57
	v_cvt_pk_bf16_f32 v65, v58, v59
	v_add_u32_e32 v68, 0, v179
	v_add_u32_e32 v70, 0, v180
	s_nop 1
	v_cvt_pk_bf16_f32 v66, v60, v61
	v_cvt_pk_bf16_f32 v67, v62, v63
	ds_write2st64_b64 v186, v[64:65], v[66:67] offset0:54 offset1:63
	s_waitcnt lgkmcnt(0)
	s_barrier
; DI float bf2f(unsigned short b) { return __uint_as_float(((unsigned)b) << 16); }
; DI unsigned short f2bf(float f) { unsigned u = __float_as_uint(f); u += 0x7fffu + ((u >> 16) & 1u); return (unsigned short)(u >> 16); }
; template <int C> DI void gdn_scan_item(const Params& p, int l, int b, int h, unsigned char* smem) {
;     ...
;         __syncthreads();
; #pragma unroll
;         for (int r = 0; r < 4; ++r) { const int i = 16 * ti + 4 * gq + r; float tot = 0.f;
; #pragma unroll
;             for (int d = 0; d < NDVG; ++d) tot += RS[i * 4 + d];
;             const float rs = rsqrtf(tot * (1.0f / 128.0f) + EPS);
; #pragma unroll
;             for (int t = 0; t < TPW; ++t) { const int dv = 16 * (dvg * TPW + t) + l15; const float sz = bf2f(szr[t][r]);
;                 MIX[(size_t)(r0c + i) * KOUT + 512 + h * 128 + dv] = f2bf(a2[t][r] * rs * nw[dv] * sz); } }
; #pragma unroll
;         for (int s = 0; s < 4; ++s) { cW[s] = nW[s]; cQ[s] = nQ[s]; }
; #pragma unroll
;         for (int t = 0; t < TPW; ++t)
; #pragma unroll
;             for (int r = 0; r < 4; ++r) cU[t][r] = nU[t][r];
	v_add_u32_e32 v66, 0, v178
	ds_read_b64 v[66:67], v66 offset:57344
	ds_read_b64 v[68:69], v68 offset:57344
	v_lshl_add_u64 v[64:65], v[126:127], 0, v[138:139]
	v_add_u32_e32 v88, 0, v181
	ds_read_b64 v[70:71], v70 offset:57344
	ds_read_b64 v[88:89], v88 offset:57344
	s_waitcnt lgkmcnt(3)
	v_mov_b32_e32 v91, v66
	s_waitcnt lgkmcnt(2)
	v_mov_b32_e32 v90, v68
	v_pk_add_f32 v[90:91], v[90:91], 0 op_sel_hi:[1,0]
	v_mov_b32_e32 v66, v69
	v_pk_add_f32 v[66:67], v[90:91], v[66:67]
	v_mov_b64_e32 v[68:69], s[4:5]
	s_brev_b32 s4, 60
	v_pk_fma_f32 v[66:67], v[66:67], s[4:5], v[68:69] op_sel_hi:[1,0,0]
	v_lshlrev_b32_e32 v91, 16, v224
	v_mul_f32_e32 v90, 0x4b800000, v67
	v_cmp_gt_f32_e32 vcc, s79, v67
	v_lshlrev_b32_e32 v97, 16, v225
	v_cndmask_b32_e32 v67, v67, v90, vcc
	v_rsq_f32_e32 v67, v67
	v_lshlrev_b32_e32 v90, 16, v223
	v_mul_f32_e32 v98, 0x45800000, v67
	v_cndmask_b32_e32 v67, v67, v98, vcc
	v_mul_f32_e32 v72, v72, v67
	v_cmp_gt_f32_e32 vcc, s79, v66
	v_mul_f32_e32 v72, v144, v72
	v_mul_f32_e32 v72, v72, v96
	v_bfe_u32 v96, v72, 16, 1
	v_add3_u32 v72, v72, v96, s59
	global_store_short_d16_hi v[64:65], v72, off
	v_mul_f32_e32 v72, v76, v67
	v_mul_f32_e32 v72, v204, v72
	v_mul_f32_e32 v72, v72, v90
	v_bfe_u32 v76, v72, 16, 1
	v_add3_u32 v72, v72, v76, s59
	global_store_short_d16_hi v[64:65], v72, off offset:32
	v_mul_f32_e32 v72, v80, v67
	v_mul_f32_e32 v72, v227, v72
	v_mul_f32_e32 v72, v72, v91
	v_bfe_u32 v76, v72, 16, 1
	v_add3_u32 v72, v72, v76, s59
	global_store_short_d16_hi v[64:65], v72, off offset:64
	v_mul_f32_e32 v72, 0x4b800000, v66
	v_mul_f32_e32 v67, v84, v67
	v_cndmask_b32_e32 v66, v66, v72, vcc
	v_mul_f32_e32 v67, v124, v67
	v_rsq_f32_e32 v66, v66
	v_mul_f32_e32 v67, v67, v97
	v_bfe_u32 v72, v67, 16, 1
	v_add3_u32 v67, v67, v72, s59
	global_store_short_d16_hi v[64:65], v67, off offset:96
	v_mul_f32_e32 v64, 0x45800000, v66
	v_cndmask_b32_e32 v66, v66, v64, vcc
	v_mul_f32_e32 v65, v73, v66
	v_lshlrev_b32_e32 v64, 16, v222
	v_mul_f32_e32 v65, v144, v65
	v_mul_f32_e32 v64, v65, v64
	v_bfe_u32 v65, v64, 16, 1
	v_add3_u32 v67, v64, v65, s59
	v_lshl_add_u64 v[64:65], v[126:127], 0, v[136:137]
	v_mul_f32_e32 v72, v77, v66
	global_store_short_d16_hi v[64:65], v67, off
	v_lshlrev_b32_e32 v67, 16, v221
	v_mul_f32_e32 v72, v204, v72
	v_mul_f32_e32 v67, v72, v67
	v_bfe_u32 v72, v67, 16, 1
	v_add3_u32 v67, v67, v72, s59
	v_mul_f32_e32 v72, v81, v66
	global_store_short_d16_hi v[64:65], v67, off offset:32
	v_lshlrev_b32_e32 v67, 16, v220
	v_mul_f32_e32 v72, v227, v72
	v_mul_f32_e32 v67, v72, v67
	v_bfe_u32 v72, v67, 16, 1
	v_add3_u32 v67, v67, v72, s59
	v_mul_f32_e32 v66, v85, v66
	global_store_short_d16_hi v[64:65], v67, off offset:64
	v_lshlrev_b32_e32 v67, 16, v219
	v_mul_f32_e32 v66, v124, v66
	v_mul_f32_e32 v66, v66, v67
	v_bfe_u32 v67, v66, 16, 1
	v_add3_u32 v66, v66, v67, s59
	global_store_short_d16_hi v[64:65], v66, off offset:96
	s_waitcnt lgkmcnt(0)
	v_mov_b32_e32 v66, v88
	v_mov_b32_e32 v67, v70
	v_pk_add_f32 v[66:67], v[66:67], 0 op_sel_hi:[1,0]
	v_mov_b32_e32 v70, v89
	v_pk_add_f32 v[66:67], v[66:67], v[70:71]
	v_lshlrev_b32_e32 v72, 16, v218
	v_pk_fma_f32 v[66:67], v[66:67], s[4:5], v[68:69] op_sel_hi:[1,0,0]
	v_lshl_add_u64 v[64:65], v[126:127], 0, v[134:135]
	v_mul_f32_e32 v68, 0x4b800000, v67
	v_cmp_gt_f32_e32 vcc, s79, v67
	v_lshlrev_b32_e32 v69, 16, v216
	v_lshlrev_b32_e32 v70, 16, v217
	v_cndmask_b32_e32 v67, v67, v68, vcc
	v_rsq_f32_e32 v67, v67
	v_lshlrev_b32_e32 v68, 16, v215
	s_mov_b64 s[4:5], 0x16000
	v_mul_f32_e32 v71, 0x45800000, v67
	v_cndmask_b32_e32 v67, v67, v71, vcc
	v_mul_f32_e32 v71, v74, v67
	v_mul_f32_e32 v71, v144, v71
	v_mul_f32_e32 v71, v71, v72
	v_bfe_u32 v72, v71, 16, 1
	v_add3_u32 v71, v71, v72, s59
	global_store_short_d16_hi v[64:65], v71, off
	v_mul_f32_e32 v71, v78, v67
	v_mul_f32_e32 v71, v204, v71
	v_mul_f32_e32 v68, v71, v68
	v_bfe_u32 v71, v68, 16, 1
	v_add3_u32 v68, v68, v71, s59
	global_store_short_d16_hi v[64:65], v68, off offset:32
	v_mul_f32_e32 v68, v82, v67
	v_mul_f32_e32 v68, v227, v68
	v_mul_f32_e32 v68, v68, v69
	v_bfe_u32 v69, v68, 16, 1
	v_add3_u32 v68, v68, v69, s59
	global_store_short_d16_hi v[64:65], v68, off offset:64
	v_mul_f32_e32 v68, 0x4b800000, v66
	v_cmp_gt_f32_e32 vcc, s79, v66
	v_mul_f32_e32 v67, v86, v67
	v_mul_f32_e32 v67, v124, v67
	v_cndmask_b32_e32 v66, v66, v68, vcc
	v_rsq_f32_e32 v66, v66
	v_mul_f32_e32 v67, v67, v70
	v_bfe_u32 v68, v67, 16, 1
	v_add3_u32 v67, v67, v68, s59
	global_store_short_d16_hi v[64:65], v67, off offset:96
	v_mul_f32_e32 v64, 0x45800000, v66
	v_cndmask_b32_e32 v66, v66, v64, vcc
	v_mul_f32_e32 v65, v75, v66
	v_lshlrev_b32_e32 v64, 16, v214
	v_mul_f32_e32 v65, v144, v65
	v_mul_f32_e32 v64, v65, v64
	v_bfe_u32 v65, v64, 16, 1
	v_add3_u32 v67, v64, v65, s59
	v_lshl_add_u64 v[64:65], v[126:127], 0, v[132:133]
	v_mul_f32_e32 v68, v79, v66
	global_store_short_d16_hi v[64:65], v67, off
	v_lshlrev_b32_e32 v67, 16, v208
	v_mul_f32_e32 v68, v204, v68
	v_mul_f32_e32 v67, v68, v67
	v_bfe_u32 v68, v67, 16, 1
	v_add3_u32 v67, v67, v68, s59
	v_mul_f32_e32 v68, v83, v66
	global_store_short_d16_hi v[64:65], v67, off offset:32
	v_lshlrev_b32_e32 v67, 16, v194
	v_mul_f32_e32 v68, v227, v68
	v_mul_f32_e32 v67, v68, v67
	v_bfe_u32 v68, v67, 16, 1
	v_add3_u32 v67, v67, v68, s59
	v_mul_f32_e32 v66, v87, v66
	global_store_short_d16_hi v[64:65], v67, off offset:64
	v_lshlrev_b32_e32 v67, 16, v191
	v_mul_f32_e32 v66, v124, v66
	v_mul_f32_e32 v66, v66, v67
	v_bfe_u32 v67, v66, 16, 1
	v_add3_u32 v66, v66, v67, s59
	v_lshl_add_u64 v[128:129], v[128:129], 0, s[4:5]
	v_lshl_add_u64 v[130:131], v[130:131], 0, s[4:5]
	global_store_short_d16_hi v[64:65], v66, off offset:96
	s_cbranch_scc0 .LBB0_684
; template <int C> DI void gdn_scan_item(const Params& p, int l, int b, int h, unsigned char* smem) {
;     ...
;         bf16x8 aK[KS2], aT[KS2]; unsigned short szr[TPW][4]; float eg; int r0c;
;         { SCAN_PTRS(n) r0c = r0; eg = ((const float*)(ws + WS_EG))[ci];
; #pragma unroll
;           for (int s = 0; s < KS2; ++s) { aK[s] = *(const bf16x8*)(QKM + (16 * ti + l15) * C + 32 * s + 8 * gq); aT[s] = *(const bf16x8*)(KDT + (16 * w + l15) * C + 32 * s + 8 * gq); }
; #pragma unroll
;           for (int t = 0; t < TPW; ++t)
; #pragma unroll
;               for (int r = 0; r < 4; ++r) szr[t][r] = QZ[(size_t)(r0 + 16 * ti + 4 * gq + r) * NQZ + 1536 + h * 128 + 16 * (dvg * TPW + t) + l15]; }
;         bf16x8 nW[4], nQ[4]; float nU[TPW][4];
;         if (n + 1 < nch) { SCAN_PTRS(n + 1)
; #pragma unroll
;           for (int s = 0; s < 4; ++s) { nW[s] = *(const bf16x8*)(Wo + (16 * ti + l15) * 128 + 32 * s + 8 * gq); nQ[s] = *(const bf16x8*)(QG + (16 * ti + l15) * 128 + 32 * s + 8 * gq); }
; #pragma unroll
;           for (int t = 0; t < TPW; ++t)
; #pragma unroll
;               for (int r = 0; r < 4; ++r) nU[t][r] = U[(16 * ti + 4 * gq + r) * 128 + 16 * (dvg * TPW + t) + l15]; }
;     ...
; #pragma unroll
;         for (int s = 0; s < 4; ++s) { cW[s] = nW[s]; cQ[s] = nQ[s]; }
; #pragma unroll
;         for (int t = 0; t < TPW; ++t)
; #pragma unroll
;             for (int r = 0; r < 4; ++r) cU[t][r] = nU[t][r];
.LBB0_680:
	s_waitcnt vmcnt(16)
	v_mov_b32_e32 v170, v197
	v_mov_b32_e32 v171, v198
	v_mov_b32_e32 v168, v187
	v_mov_b32_e32 v169, v188
	v_mov_b32_e32 v166, v199
	v_mov_b32_e32 v167, v209
	v_mov_b32_e32 v164, v189
	v_mov_b32_e32 v165, v190
	v_mov_b32_e32 v162, v210
	v_mov_b32_e32 v163, v211
	v_mov_b32_e32 v160, v192
	v_mov_b32_e32 v161, v193
	v_mov_b32_e32 v158, v213
	v_mov_b32_e32 v159, v212
	v_mov_b32_e32 v156, v196
	v_mov_b32_e32 v157, v195
	v_mov_b64_e32 v[102:103], v[18:19]
	v_mov_b64_e32 v[106:107], v[2:3]
	v_mov_b64_e32 v[100:101], v[16:17]
	v_mov_b64_e32 v[104:105], v[0:1]
	v_mov_b64_e32 v[90:91], v[22:23]
	v_mov_b64_e32 v[82:83], v[30:31]
	v_mov_b64_e32 v[74:75], v[26:27]
	v_mov_b64_e32 v[94:95], v[6:7]
	v_mov_b64_e32 v[86:87], v[10:11]
	v_mov_b64_e32 v[78:79], v[14:15]
	v_mov_b64_e32 v[88:89], v[20:21]
	v_mov_b64_e32 v[80:81], v[28:29]
	v_mov_b64_e32 v[72:73], v[24:25]
	v_mov_b64_e32 v[92:93], v[4:5]
	v_mov_b64_e32 v[84:85], v[8:9]
	v_mov_b64_e32 v[76:77], v[12:13]
	s_add_u32 s4, s10, s12
	v_add_u32_e32 v132, s0, v182
	s_addc_u32 s5, s11, s13
	v_add_u32_e32 v134, 1, v132
	global_load_dword v154, v141, s[4:5]
	v_lshl_add_u64 v[64:65], s[10:11], 0, v[128:129]
	s_mov_b32 s4, 0xc115000
	v_ashrrev_i32_e32 v133, 31, v132
	v_ashrrev_i32_e32 v135, 31, v134
	v_add_co_u32_e32 v64, vcc, s4, v64
	v_lshlrev_b64 v[138:139], 12, v[132:133]
	v_lshlrev_b64 v[136:137], 12, v[134:135]
	v_add_u32_e32 v134, 2, v132
	v_add_u32_e32 v132, 3, v132
	v_lshl_add_u64 v[66:67], s[10:11], 0, v[130:131]
	v_addc_co_u32_e32 v65, vcc, 0, v65, vcc
	s_mov_b32 s4, 0xc111000
	v_ashrrev_i32_e32 v133, 31, v132
	v_add_co_u32_e32 v66, vcc, s4, v66
	v_ashrrev_i32_e32 v135, 31, v134
	v_lshlrev_b64 v[132:133], 12, v[132:133]
	v_addc_co_u32_e32 v67, vcc, 0, v67, vcc
	v_lshl_add_u64 v[146:147], v[122:123], 0, v[138:139]
	v_lshlrev_b64 v[134:135], 12, v[134:135]
	v_lshl_add_u64 v[190:191], v[122:123], 0, v[132:133]
	global_load_dwordx4 v[108:111], v[64:65], off
	global_load_dwordx4 v[96:99], v[64:65], off offset:64
	global_load_dwordx4 v[68:71], v[66:67], off
	s_nop 0
	global_load_dwordx4 v[64:67], v[66:67], off offset:64
	v_lshl_add_u64 v[148:149], v[122:123], 0, v[136:137]
	v_lshl_add_u64 v[188:189], v[122:123], 0, v[134:135]
	global_load_ushort v226, v[146:147], off
	global_load_ushort v222, v[148:149], off
	global_load_ushort v223, v[146:147], off offset:32
	global_load_ushort v221, v[148:149], off offset:32
	global_load_ushort v224, v[146:147], off offset:64
	global_load_ushort v220, v[148:149], off offset:64
	global_load_ushort v219, v[148:149], off offset:96
	global_load_ushort v225, v[146:147], off offset:96
	global_load_ushort v218, v[188:189], off
	global_load_ushort v214, v[190:191], off
	global_load_ushort v215, v[188:189], off offset:32
	global_load_ushort v208, v[190:191], off offset:32
	global_load_ushort v216, v[188:189], off offset:64
	global_load_ushort v194, v[190:191], off offset:64
	s_nop 0
	global_load_ushort v191, v[190:191], off offset:96
	s_nop 0
	global_load_ushort v217, v[188:189], off offset:96
	s_cmpk_eq_i32 s0, 0xfc0
	s_nop 0
	s_mul_i32 s4, s17, 0x16000
	s_mul_hi_i32 s5, s17, 0x16000
	s_add_u32 s4, s1, s4
	s_addc_u32 s5, s16, s5
	v_lshl_add_u64 v[0:1], v[112:113], 1, s[4:5]
	v_lshl_add_u64 v[0:1], v[0:1], 0, v[140:141]
	v_add_co_u32_e32 v2, vcc, 0x8000, v0
	s_mov_b64 s[14:15], 0x8000
	s_nop 0
	v_addc_co_u32_e32 v3, vcc, 0, v1, vcc
	v_lshl_add_u64 v[12:13], v[0:1], 0, s[14:15]
	s_mov_b64 s[14:15], 0xc000
	v_add_co_u32_e32 v4, vcc, 0xc000, v0
	v_lshl_add_u64 v[24:25], v[0:1], 0, s[14:15]
	s_nop 0
	v_addc_co_u32_e32 v5, vcc, 0, v1, vcc
	v_lshl_add_u64 v[146:147], v[114:115], 2, s[4:5]
	v_lshl_add_u64 v[212:213], v[120:121], 2, s[4:5]
	global_load_dwordx4 v[0:3], v[2:3], off
	s_nop 0
	global_load_dwordx4 v[16:19], v[4:5], off
	s_nop 0
	global_load_dwordx4 v[4:7], v[12:13], off offset:64
	global_load_dwordx4 v[8:11], v[12:13], off offset:128
	global_load_dwordx4 v[20:23], v[24:25], off offset:64
	s_nop 0
	global_load_dwordx4 v[12:15], v[12:13], off offset:192
	s_nop 0
	global_load_dwordx4 v[28:31], v[24:25], off offset:128
	s_nop 0
	global_load_dwordx4 v[24:27], v[24:25], off offset:192
	v_lshl_add_u64 v[148:149], v[116:117], 2, s[4:5]
	v_lshl_add_u64 v[228:229], v[118:119], 2, s[4:5]
	global_load_dword v187, v[146:147], off
	global_load_dword v188, v[148:149], off
	global_load_dword v189, v[146:147], off offset:64
	global_load_dword v190, v[148:149], off offset:64
	global_load_dword v192, v[146:147], off offset:128
	global_load_dword v193, v[148:149], off offset:128
	global_load_dword v195, v[148:149], off offset:192
	global_load_dword v196, v[146:147], off offset:192
	global_load_dword v197, v[228:229], off
	global_load_dword v198, v[212:213], off
	global_load_dword v199, v[228:229], off offset:64
	global_load_dword v209, v[212:213], off offset:64
	global_load_dword v210, v[228:229], off offset:128
	global_load_dword v211, v[212:213], off offset:128
	s_nop 0
	global_load_dword v212, v[212:213], off offset:192
	s_nop 0
	global_load_dword v213, v[228:229], off offset:192
